# sample-MLA: the wave without score duty also issues its partner's two non-urgent latent-tile DMAs; parity-dependent vmcnt at step top
# baseline (speedup 1.0000x reference)
.LBB0_1104:
	s_mul_i32 s12, s56, 0x2800
	s_ashr_i32 s67, s66, 31
	s_mul_hi_i32 s9, s56, 0x2800
	s_add_u32 s12, s66, s12
	s_addc_u32 s13, s67, s9
	s_lshl_b64 s[12:13], s[12:13], 8
	v_readlane_b32 s9, v254, 13
	s_add_u32 s9, s9, s12
	v_readlane_b32 s12, v254, 14
	s_addc_u32 s12, s12, s13
	s_add_u32 s16, s9, 0x200000
	s_addc_u32 s57, s12, 0
	s_ashr_i32 s69, s68, 31
	s_lshl_b64 s[12:13], s[68:69], 10
	v_readlane_b32 s9, v254, 40
	s_add_u32 s76, s9, s12
	v_readlane_b32 s9, v254, 41
	s_addc_u32 s77, s9, s13
	s_lshl_b64 s[12:13], s[68:69], 7
	v_readlane_b32 s18, v254, 11
	v_readlane_b32 s19, v254, 12
	s_add_u32 s37, s18, s12
	s_addc_u32 s55, s19, s13
	s_mul_i32 s9, s50, 0x14000
	v_readlane_b32 s12, v255, 20
	v_readlane_b32 s13, v255, 21
	s_add_u32 s9, s12, s9
	s_addc_u32 s18, s13, 0
	s_lshl_b64 s[12:13], s[66:67], 2
	s_add_u32 s9, s9, s12
	v_lshlrev_b32_e32 v4, 1, v25
	s_addc_u32 s13, s18, s13
	v_and_b32_e32 v237, 0xc0, v27
	v_and_b32_e32 v238, 32, v4
	v_and_b32_e32 v239, 0x100, v28
	v_bfe_i32 v4, v214, 4, 1
	s_movk_i32 s1, 0x2800
	s_add_u32 s12, s9, 0x7b152000
	v_readlane_b32 s9, v255, 27
	v_and_or_b32 v4, v4, s1, v7
	s_addc_u32 s36, s13, 0
	v_add3_u32 v7, s9, v239, v237
	v_readlane_b32 s9, v255, 26
	v_add3_u32 v240, v7, v238, v224
	s_add_u32 s64, s64, 0x10000
	v_add3_u32 v7, s9, v239, v237
	v_add3_u32 v241, v7, v238, v224
	v_mov_b32_e32 v7, 0x1b980
	v_mov_b32_e32 v8, 0x19100
	v_or_b32_e32 v217, 32, v198
	v_or_b32_e32 v216, 64, v198
	v_or_b32_e32 v199, 0x60, v198
	s_mov_b32 s17, 1
	s_mov_b32 s1, 2
	v_lshlrev_b32_e32 v4, 2, v4
	s_mov_b32 s28, 7
	v_lshl_or_b32 v5, v24, 8, v26
	s_addc_u32 s65, s65, 0
	s_mov_b32 s25, 0
	s_mov_b32 s13, 6
	s_mov_b32 s86, 4
	s_mov_b32 s87, 3
	v_cndmask_b32_e64 v242, v7, v8, s[48:49]
	s_mov_b32 s9, 0
	s_mov_b32 s81, 0
	s_mov_b32 s18, 0
	v_mov_b32_e32 v7, v6
	v_mov_b32_e32 v8, v6
	v_mov_b32_e32 v9, v6
	v_mov_b32_e32 v10, v6
	v_mov_b32_e32 v11, v6
	v_mov_b32_e32 v12, v6
	v_mov_b32_e32 v13, v6
	v_mov_b32_e32 v14, v6
	v_mov_b32_e32 v15, v6
	v_mov_b32_e32 v16, v6
	v_mov_b32_e32 v17, v6
	v_mov_b32_e32 v18, v6
	v_mov_b32_e32 v19, v6
	v_mov_b32_e32 v20, v6
	v_mov_b32_e32 v21, v6
	v_mov_b32_e32 v118, v6
	v_mov_b32_e32 v119, v6
	v_mov_b32_e32 v120, v6
	v_mov_b32_e32 v121, v6
	v_mov_b32_e32 v122, v6
	v_mov_b32_e32 v123, v6
	v_mov_b32_e32 v124, v6
	v_mov_b32_e32 v125, v6
	v_mov_b32_e32 v126, v6
	v_mov_b32_e32 v127, v6
	v_mov_b32_e32 v128, v6
	v_mov_b32_e32 v129, v6
	v_mov_b32_e32 v130, v6
	v_mov_b32_e32 v131, v6
	v_mov_b32_e32 v132, v6
	v_mov_b32_e32 v133, v6
	v_mov_b32_e32 v102, v6
	v_mov_b32_e32 v103, v6
	v_mov_b32_e32 v104, v6
	v_mov_b32_e32 v105, v6
	v_mov_b32_e32 v106, v6
	v_mov_b32_e32 v107, v6
	v_mov_b32_e32 v108, v6
	v_mov_b32_e32 v109, v6
	v_mov_b32_e32 v110, v6
	v_mov_b32_e32 v111, v6
	v_mov_b32_e32 v112, v6
	v_mov_b32_e32 v113, v6
	v_mov_b32_e32 v114, v6
	v_mov_b32_e32 v115, v6
	v_mov_b32_e32 v116, v6
	v_mov_b32_e32 v117, v6
	v_mov_b32_e32 v86, v6
	v_mov_b32_e32 v87, v6
	v_mov_b32_e32 v88, v6
	v_mov_b32_e32 v89, v6
	v_mov_b32_e32 v90, v6
	v_mov_b32_e32 v91, v6
	v_mov_b32_e32 v92, v6
	v_mov_b32_e32 v93, v6
	v_mov_b32_e32 v94, v6
	v_mov_b32_e32 v95, v6
	v_mov_b32_e32 v96, v6
	v_mov_b32_e32 v97, v6
	v_mov_b32_e32 v98, v6
	v_mov_b32_e32 v99, v6
	v_mov_b32_e32 v100, v6
	v_mov_b32_e32 v101, v6
	v_mov_b32_e32 v70, v6
	v_mov_b32_e32 v71, v6
	v_mov_b32_e32 v72, v6
	v_mov_b32_e32 v73, v6
	v_mov_b32_e32 v74, v6
	v_mov_b32_e32 v75, v6
	v_mov_b32_e32 v76, v6
	v_mov_b32_e32 v77, v6
	v_mov_b32_e32 v78, v6
	v_mov_b32_e32 v79, v6
	v_mov_b32_e32 v80, v6
	v_mov_b32_e32 v81, v6
	v_mov_b32_e32 v82, v6
	v_mov_b32_e32 v83, v6
	v_mov_b32_e32 v84, v6
	v_mov_b32_e32 v85, v6
	v_mov_b32_e32 v54, v6
	v_mov_b32_e32 v55, v6
	v_mov_b32_e32 v56, v6
	v_mov_b32_e32 v57, v6
	v_mov_b32_e32 v58, v6
	v_mov_b32_e32 v59, v6
	v_mov_b32_e32 v60, v6
	v_mov_b32_e32 v61, v6
	v_mov_b32_e32 v62, v6
	v_mov_b32_e32 v63, v6
	v_mov_b32_e32 v64, v6
	v_mov_b32_e32 v65, v6
	v_mov_b32_e32 v66, v6
	v_mov_b32_e32 v67, v6
	v_mov_b32_e32 v68, v6
	v_mov_b32_e32 v69, v6
	v_mov_b32_e32 v38, v6
	v_mov_b32_e32 v39, v6
	v_mov_b32_e32 v40, v6
	v_mov_b32_e32 v41, v6
	v_mov_b32_e32 v42, v6
	v_mov_b32_e32 v43, v6
	v_mov_b32_e32 v44, v6
	v_mov_b32_e32 v45, v6
	v_mov_b32_e32 v46, v6
	v_mov_b32_e32 v47, v6
	v_mov_b32_e32 v48, v6
	v_mov_b32_e32 v49, v6
	v_mov_b32_e32 v50, v6
	v_mov_b32_e32 v51, v6
	v_mov_b32_e32 v52, v6
	v_mov_b32_e32 v53, v6
	v_mov_b32_e32 v22, v6
	v_mov_b32_e32 v23, v6
	v_mov_b32_e32 v24, v6
	v_mov_b32_e32 v25, v6
	v_mov_b32_e32 v26, v6
	v_mov_b32_e32 v27, v6
	v_mov_b32_e32 v28, v6
	v_mov_b32_e32 v29, v6
	v_mov_b32_e32 v30, v6
	v_mov_b32_e32 v31, v6
	v_mov_b32_e32 v32, v6
	v_mov_b32_e32 v33, v6
	v_mov_b32_e32 v34, v6
	v_mov_b32_e32 v35, v6
	v_mov_b32_e32 v36, v6
	v_mov_b32_e32 v37, v6
	v_readfirstlane_b32 s19, v0
	s_bitcmp1_b32 s19, 8
	s_cselect_b32 s23, -1, 0
	s_movk_i32 s20, 0x2000
	s_xor_b32 s20, s20, s23
	s_sub_i32 s20, s20, s23
	s_movk_i32 s21, 0x1000
	s_xor_b32 s21, s21, s23
	s_sub_i32 s21, s21, s23
	v_writelane_b32 v255, s20, 37
	v_writelane_b32 v255, s21, 38
	v_writelane_b32 v255, s23, 39
	s_nop 0
	s_branch .LBB0_1106

.LBB0_1106:
	s_cmp_eq_u32 s18, 0
	s_cbranch_scc1 .Lw_orig
	s_add_i32 s19, s92, s18
	s_and_b32 s19, s19, 1
	s_cmp_eq_u32 s3, s19
	s_cbranch_scc1 .Lw_mine
	s_and_b64 vcc, exec, s[34:35]
	s_cbranch_vccz .Lw_b8
	s_waitcnt vmcnt(6)
	s_branch .LBB0_1110
.Lw_b8:
	s_waitcnt vmcnt(8)
	s_branch .LBB0_1110
.Lw_mine:
	s_and_b64 vcc, exec, s[34:35]
	s_cbranch_vccz .Lw_m4
	s_waitcnt vmcnt(2)
	s_branch .LBB0_1110
.Lw_m4:
	s_waitcnt vmcnt(4)
	s_branch .LBB0_1110

.LBB0_1116:
	s_cmp_eq_u32 s18, 0x7f
	s_cbranch_scc1 .Lc4_go
	s_cmp_lg_u64 s[66:67], 0
	s_cbranch_scc1 .LBB0_1120
.Lc4_go:
	s_mul_hi_u32 s19, s86, 0xcccccccd
	s_lshr_b32 s19, s19, 2
	s_mul_i32 s20, s19, 0x14000
	s_sub_i32 s19, s31, s20
	s_sub_i32 s20, s30, s20
	s_cmpk_gt_u32 s18, 0x7d
	s_mov_b64 s[70:71], -1
	s_cbranch_scc0 .LBB0_1118
	s_add_i32 s78, s28, 0xfffffefd
	s_lshl_b64 s[70:71], s[78:79], 14
	s_add_u32 s70, s76, s70
	s_addc_u32 s71, s77, s71
	s_add_i32 s21, s9, 0
	s_add_i32 s22, s21, s20
	s_mov_b32 m0, s22
	s_nop 0
	global_load_lds_dwordx4 v220, s[70:71]
	s_add_i32 s21, s21, s19
	s_mov_b32 m0, s21
	s_nop 0
	global_load_lds_dwordx4 v221, s[70:71]
	s_cmp_eq_u32 s18, 0x7f
	s_cbranch_scc1 .Lc4_np_a
	v_readlane_b32 s98, v255, 38
	v_readlane_b32 s99, v255, 39
	s_add_u32 s72, s70, s98
	s_addc_u32 s73, s71, s99
	v_readlane_b32 s98, v255, 37
	s_add_i32 s23, s22, s98
	s_mov_b32 m0, s23
	s_nop 0
	global_load_lds_dwordx4 v220, s[72:73]
	s_add_i32 s23, s21, s98
	s_mov_b32 m0, s23
	s_nop 0
	global_load_lds_dwordx4 v221, s[72:73]
.Lc4_np_a:
	s_mov_b64 s[70:71], 0
.LBB0_1118:
	s_andn2_b64 vcc, exec, s[70:71]
	s_cbranch_vccnz .LBB0_1120
	s_add_i32 s21, s9, 0
	s_add_i32 s20, s21, s20
	s_mov_b32 m0, s20
	s_nop 0
	global_load_lds_dwordx4 v220, s[64:65]
	s_add_i32 s21, s21, s19
	s_mov_b32 m0, s21
	s_nop 0
	global_load_lds_dwordx4 v221, s[64:65]
	s_cmp_eq_u32 s18, 0x7f
	s_cbranch_scc1 .Lc4_np_b
	v_readlane_b32 s98, v255, 38
	v_readlane_b32 s99, v255, 39
	s_add_u32 s72, s64, s98
	s_addc_u32 s73, s65, s99
	v_readlane_b32 s98, v255, 37
	s_add_i32 s23, s20, s98
	s_mov_b32 m0, s23
	s_nop 0
	global_load_lds_dwordx4 v220, s[72:73]
	s_add_i32 s23, s21, s98
	s_mov_b32 m0, s23
	s_nop 0
	global_load_lds_dwordx4 v221, s[72:73]
.Lc4_np_b:
.LBB0_1120:
	s_mul_hi_u32 s19, s13, 0xaaaaaaab
	s_lshr_b32 s20, s19, 2
	s_mul_i32 s20, s20, 0xf300
	s_sub_i32 s21, 0x25b00, s20
	s_sub_i32 s19, 0x25300, s20
	s_sub_i32 s84, 0x23300, s20
	s_add_i32 s22, s28, -1
	s_and_b64 s[70:71], s[68:69], exec
	s_cselect_b32 s78, s22, 0x103
	s_cmpk_gt_u32 s78, 0xff
	s_mov_b64 s[70:71], -1
	s_cbranch_scc0 .LBB0_1126
	s_add_i32 s70, s78, 0xffffff00
	s_mov_b32 s71, s79
	s_lshl_b64 s[22:23], s[70:71], 12
	s_add_u32 s22, s16, s22
	s_addc_u32 s23, s57, s23
	s_add_i32 s72, s40, s81
	s_add_i32 s73, s72, s84
	s_mov_b32 m0, s73
	s_nop 0
	global_load_lds_dwordx4 v5, s[22:23]
	s_and_b64 vcc, exec, s[46:47]
	s_cbranch_vccnz .LBB0_1123
	s_add_i32 s72, s72, s19
	s_lshl_b64 s[22:23], s[70:71], 11
	s_add_u32 s22, s37, s22
	s_addc_u32 s23, s55, s23
	s_mov_b32 m0, s72
	s_nop 0
	global_load_lds_dwordx4 v219, s[22:23]

.Lpv_prio_done:
	ds_read_b64_tr_b16 v[204:205], v200 offset:1536
	ds_read_b64_tr_b16 v[206:207], v200 offset:9728
	s_waitcnt lgkmcnt(6)
	v_mfma_f32_32x32x16_bf16 v[6:21], v[138:141], v[142:145], v[6:21]
	ds_read_b64_tr_b16 v[142:143], v200 offset:2048
	ds_read_b64_tr_b16 v[144:145], v200 offset:10240
	s_waitcnt lgkmcnt(6)
	v_mfma_f32_32x32x16_bf16 v[118:133], v[138:141], v[146:149], v[118:133]
	ds_read_b64_tr_b16 v[146:147], v200 offset:2560
	ds_read_b64_tr_b16 v[148:149], v200 offset:10752
	s_waitcnt lgkmcnt(6)
	v_mfma_f32_32x32x16_bf16 v[102:117], v[138:141], v[248:251], v[102:117]
	ds_read_b64_tr_b16 v[248:249], v200 offset:3072
	ds_read_b64_tr_b16 v[250:251], v200 offset:11264
	s_waitcnt lgkmcnt(6)
	v_mfma_f32_32x32x16_bf16 v[86:101], v[138:141], v[204:207], v[86:101]
	ds_read_b64_tr_b16 v[204:205], v200 offset:3584
	ds_read_b64_tr_b16 v[206:207], v200 offset:11776
	s_waitcnt lgkmcnt(6)
	v_mfma_f32_32x32x16_bf16 v[70:85], v[138:141], v[142:145], v[70:85]
	ds_read_b64_tr_b16 v[142:143], v1 offset:0
	ds_read_b64_tr_b16 v[144:145], v1 offset:8192
	s_waitcnt lgkmcnt(6)
	v_mfma_f32_32x32x16_bf16 v[54:69], v[138:141], v[146:149], v[54:69]
	ds_read_b64_tr_b16 v[146:147], v1 offset:512
	ds_read_b64_tr_b16 v[148:149], v1 offset:8704
	s_waitcnt lgkmcnt(6)
	v_mfma_f32_32x32x16_bf16 v[38:53], v[138:141], v[248:251], v[38:53]
	ds_read_b64_tr_b16 v[248:249], v1 offset:1024
	ds_read_b64_tr_b16 v[250:251], v1 offset:9216
	s_waitcnt lgkmcnt(6)
	v_mfma_f32_32x32x16_bf16 v[22:37], v[138:141], v[204:207], v[22:37]
	ds_read_b64_tr_b16 v[204:205], v1 offset:1536
	ds_read_b64_tr_b16 v[206:207], v1 offset:9728
	s_waitcnt lgkmcnt(6)
	v_mfma_f32_32x32x16_bf16 v[6:21], v[134:137], v[142:145], v[6:21]
	ds_read_b64_tr_b16 v[142:143], v1 offset:2048
	ds_read_b64_tr_b16 v[144:145], v1 offset:10240
	s_waitcnt lgkmcnt(6)
	v_mfma_f32_32x32x16_bf16 v[118:133], v[134:137], v[146:149], v[118:133]
	ds_read_b64_tr_b16 v[146:147], v1 offset:2560
	ds_read_b64_tr_b16 v[148:149], v1 offset:10752
	s_waitcnt lgkmcnt(6)
	v_mfma_f32_32x32x16_bf16 v[102:117], v[134:137], v[248:251], v[102:117]
	ds_read_b64_tr_b16 v[248:249], v1 offset:3072
	ds_read_b64_tr_b16 v[250:251], v1 offset:11264
	s_waitcnt lgkmcnt(6)
	v_mfma_f32_32x32x16_bf16 v[86:101], v[134:137], v[204:207], v[86:101]
	ds_read_b64_tr_b16 v[204:205], v1 offset:3584
	ds_read_b64_tr_b16 v[206:207], v1 offset:11776
	s_waitcnt lgkmcnt(6)
	v_mfma_f32_32x32x16_bf16 v[70:85], v[134:137], v[142:145], v[70:85]
	s_waitcnt lgkmcnt(4)
	v_mfma_f32_32x32x16_bf16 v[54:69], v[134:137], v[146:149], v[54:69]
	s_waitcnt lgkmcnt(2)
	v_mfma_f32_32x32x16_bf16 v[38:53], v[134:137], v[248:251], v[38:53]
	s_waitcnt lgkmcnt(0)
	v_mfma_f32_32x32x16_bf16 v[22:37], v[134:137], v[204:207], v[22:37]
	s_setprio 0
	s_andn2_b64 vcc, exec, s[66:67]
	s_cbranch_vccnz .LBB0_1105
	s_mul_hi_u32 s19, s1, 0xaaaaaaab
	s_lshr_b32 s19, s19, 2
	s_mul_i32 s19, s19, 0xffff0d00
	s_add_i32 s19, s19, 0
	s_add_i32 s19, s19, s81
	v_add_u32_e32 v1, s19, v242
	v_add_u32_e32 v200, s14, v1
	v_add3_u32 v134, v200, v231, v232
	v_add3_u32 v138, v200, v230, v232
	ds_read_b128 v[134:137], v134
	ds_read_b128 v[204:207], v138
	v_add3_u32 v208, v200, v228, v232
	ds_read_b128 v[248:251], v208
	s_setprio 1
	s_waitcnt lgkmcnt(2)
	v_mfma_f32_32x32x16_bf16 v[134:149], v[134:137], v[194:197], 0
	s_waitcnt lgkmcnt(1)
	v_mfma_f32_32x32x16_bf16 v[134:149], v[204:207], v[190:193], v[134:149]
	v_add3_u32 v208, v200, v227, v232
	ds_read_b128 v[204:207], v208
	s_waitcnt lgkmcnt(1)
	v_mfma_f32_32x32x16_bf16 v[134:149], v[248:251], v[186:189], v[134:149]
	v_add3_u32 v208, v200, v236, v232
	ds_read_b128 v[248:251], v208
	s_waitcnt lgkmcnt(1)
	v_mfma_f32_32x32x16_bf16 v[134:149], v[204:207], v[182:185], v[134:149]
	v_add3_u32 v208, v200, v235, v232
	ds_read_b128 v[204:207], v208
	s_waitcnt lgkmcnt(1)
	v_mfma_f32_32x32x16_bf16 v[134:149], v[248:251], v[178:181], v[134:149]
	v_add3_u32 v208, v200, v234, v232
	ds_read_b128 v[248:251], v208
	s_waitcnt lgkmcnt(1)
	v_mfma_f32_32x32x16_bf16 v[134:149], v[204:207], v[174:177], v[134:149]
	v_add3_u32 v208, v200, v233, v232
	ds_read_b128 v[204:207], v208
	s_waitcnt lgkmcnt(1)
	v_mfma_f32_32x32x16_bf16 v[134:149], v[248:251], v[170:173], v[134:149]
	v_add3_u32 v208, v1, v231, v226
	ds_read_b128 v[248:251], v208 offset:8192
	s_waitcnt lgkmcnt(1)
	v_mfma_f32_32x32x16_bf16 v[134:149], v[204:207], v[166:169], v[134:149]
	v_add3_u32 v208, v1, v230, v226
	ds_read_b128 v[204:207], v208 offset:8192
	s_waitcnt lgkmcnt(1)
	v_mfma_f32_32x32x16_bf16 v[134:149], v[248:251], v[162:165], v[134:149]
	v_add3_u32 v208, v1, v228, v226
	ds_read_b128 v[248:251], v208 offset:8192
	s_waitcnt lgkmcnt(1)
	v_mfma_f32_32x32x16_bf16 v[134:149], v[204:207], v[158:161], v[134:149]
	v_add3_u32 v208, v1, v227, v226
	ds_read_b128 v[204:207], v208 offset:8192
	s_waitcnt lgkmcnt(1)
	v_mfma_f32_32x32x16_bf16 v[134:149], v[248:251], v[154:157], v[134:149]
	s_waitcnt lgkmcnt(0)
	v_mfma_f32_32x32x16_bf16 v[134:149], v[204:207], v[150:153], v[134:149]
	s_setprio 0
	v_add_u32_e32 v1, s15, v198
	v_add_u32_e32 v208, s19, v1
	v_add_u32_e32 v1, 0x1b900, v208
	ds_read_b128 v[204:207], v1
	v_add_u32_e32 v1, 0x1b920, v208
	ds_read_b128 v[248:251], v1
	s_waitcnt lgkmcnt(1)
	s_nop 5
	v_fma_f32 v1, v134, v204, -v213
	v_fma_f32 v134, v135, v205, -v213
	v_exp_f32_e32 v1, v1
	v_fma_f32 v135, v136, v206, -v213
	v_exp_f32_e32 v200, v134
	v_fma_f32 v136, v137, v207, -v213
	v_exp_f32_e32 v204, v135
	v_exp_f32_e32 v205, v136
	s_waitcnt lgkmcnt(0)
	v_fma_f32 v135, v138, v248, -v213
	v_add_f32_e32 v134, 0, v1
	v_exp_f32_e32 v206, v135
	v_add_f32_e32 v134, v200, v134
	v_add_f32_e32 v134, v204, v134
	v_add_f32_e32 v134, v205, v134
	v_add_f32_e32 v138, v206, v134
	v_fma_f32 v134, v139, v249, -v213
	v_exp_f32_e32 v207, v134
	v_fma_f32 v134, v140, v250, -v213
	v_exp_f32_e32 v248, v134
	v_fma_f32 v134, v141, v251, -v213
	v_exp_f32_e32 v249, v134
	v_add_u32_e32 v139, 0x1e180, v208
	v_add_f32_e32 v138, v207, v138
	ds_read_b128 v[134:137], v139
	v_add_f32_e32 v138, v248, v138
	v_add_f32_e32 v208, v249, v138
	ds_read_b128 v[138:141], v139 offset:32
	s_waitcnt lgkmcnt(1)
	v_fma_f32 v134, v142, v134, -v213
	v_exp_f32_e32 v134, v134
	v_fma_f32 v135, v143, v135, -v213
	s_waitcnt lgkmcnt(0)
	v_fma_f32 v138, v146, v138, -v213
	v_exp_f32_e32 v135, v135
	v_fma_f32 v136, v144, v136, -v213
	v_exp_f32_e32 v143, v138
	v_fma_f32 v138, v147, v139, -v213
	v_exp_f32_e32 v136, v136
	v_fma_f32 v137, v145, v137, -v213
	v_exp_f32_e32 v144, v138
	v_fma_f32 v138, v148, v140, -v213
	v_exp_f32_e32 v137, v137
	v_exp_f32_e32 v145, v138
	v_fma_f32 v138, v149, v141, -v213
	v_add_f32_e32 v142, v134, v208
	v_exp_f32_e32 v146, v138
	v_add_f32_e32 v142, v135, v142
	v_add_f32_e32 v142, v136, v142
	v_add_f32_e32 v142, v137, v142
	v_cvt_pk_bf16_f32 v138, v1, v200
	v_cvt_pk_bf16_f32 v139, v204, v205
	v_cvt_pk_bf16_f32 v140, v206, v207
	v_cvt_pk_bf16_f32 v141, v248, v249
	s_nop 0
	v_permlane32_swap_b32_e32 v138, v140
	v_permlane32_swap_b32_e32 v139, v141
	v_cvt_pk_bf16_f32 v134, v134, v135
	v_cvt_pk_bf16_f32 v135, v136, v137
	v_cvt_pk_bf16_f32 v136, v143, v144
	v_cvt_pk_bf16_f32 v137, v145, v146
	v_add_f32_e32 v1, v143, v142
	v_permlane32_swap_b32_e32 v134, v136
	v_permlane32_swap_b32_e32 v135, v137
	v_add_f32_e32 v1, v144, v1
	ds_write_b128 v223, v[138:141]
	ds_write_b128 v223, v[134:137] offset:16
	v_add_f32_e32 v1, v145, v1
	s_waitcnt lgkmcnt(0)
	v_add_f32_e32 v1, v146, v1
	v_add_f32_e32 v2, v2, v1
	s_branch .LBB0_1105
	s_nop 0
	s_nop 0
	s_nop 0
	s_nop 0
	s_nop 0
	s_nop 0
	s_nop 0
	s_nop 0
	s_nop 0
	s_nop 0
	s_nop 0
	s_nop 0
	s_nop 0
	s_nop 0
	s_nop 0
	s_nop 0
	s_nop 0
	s_nop 0
	s_nop 0
	s_nop 0
	s_nop 0
	s_nop 0
	s_nop 0
	s_nop 0
	s_nop 0
